# v065: v056 + L2 warm-up of the first K/V tiles at the start of each prompt MLA unit
# baseline (speedup 1.0000x reference)
.LBB0_1154:
	s_cmp_lg_u32 s62, 2
	v_readlane_b32 s14, v253, 12
	s_cselect_b64 s[0:1], -1, 0
	v_readlane_b32 s15, v253, 13
	s_or_b64 s[0:1], s[14:15], s[0:1]
	s_and_b64 s[0:1], s[0:1], exec
	v_readlane_b32 s0, v253, 8
	s_cselect_b32 s0, s9, s0
	s_cmpk_gt_u32 s0, 0x2ff
	s_cbranch_scc1 .LBB0_1149
	s_and_b32 s1, s0, 0xffff
	s_mul_i32 s1, s1, 0xaaab
	s_lshr_b32 s24, s1, 22
	s_mul_i32 s1, s24, 0x60
	s_sub_i32 s0, s0, s1
	s_mul_i32 s1, s0, 0xab
	s_bfe_u32 s18, s1, 0x5000b
	s_mul_i32 s8, s18, 12
	s_sub_i32 s0, s0, s8
	s_and_b32 s74, s0, 0xff
	s_and_b32 s0, s1, 0xf800
	s_lshl_b32 s1, s24, 8
	s_sub_i32 s25, 0x700, s1
	s_or_b32 s64, s0, s25
	s_mul_i32 s0, s64, 12
	s_or_b32 s0, s0, s74
	s_mul_hi_u32 s1, s0, 0xc0
	s_mulk_i32 s0, 0xc0
	s_add_u32 s0, s82, s0
	s_addc_u32 s1, s83, s1
	s_add_i32 s8, s90, s74
	s_mul_i32 s68, s8, 0x4100
	s_lshl_b64 s[8:9], s[68:69], 2
	v_mov_b32_e32 v54, v0
	s_add_u32 s8, s86, s8
	s_addc_u32 s9, s87, s9
	v_ashrrev_i32_e32 v52, 6, v54
	s_lshl_b32 s14, s64, 2
	v_and_b32_e32 v55, 31, v54
	v_lshlrev_b32_e32 v53, 5, v52
	s_add_u32 s8, s8, s14
	s_waitcnt lgkmcnt(0)
	v_or_b32_e32 v1, v53, v55
	s_movk_i32 s14, 0x100
	v_cmp_gt_i32_e64 s[14:15], s14, v1
	s_addc_u32 s9, s9, 0
	v_bfe_u32 v56, v54, 5, 1
	v_cndmask_b32_e64 v162, v230, v1, s[14:15]
	v_ashrrev_i32_e32 v163, 31, v162
	v_lshl_add_u64 v[4:5], v[162:163], 2, s[8:9]
	global_load_dword v1, v[4:5], off
	v_mov_b64_e32 v[4:5], s[0:1]
	v_mad_i64_i32 v[4:5], s[0:1], v162, s70, v[4:5]
	v_lshlrev_b32_e32 v50, 4, v56
	v_mov_b32_e32 v51, v2
	v_lshl_add_u64 v[40:41], v[4:5], 0, v[50:51]
	v_add_lshl_u32 v4, v162, s25, 4
	v_ashrrev_i32_e32 v5, 31, v4
	v_lshlrev_b64 v[4:5], 2, v[4:5]
	v_lshl_add_u64 v[6:7], s[6:7], 0, v[4:5]
	v_and_b32_e32 v8, 32, v54
	v_mov_b32_e32 v9, v2
	v_lshl_add_u64 v[4:5], s[80:81], 0, v[4:5]
	v_lshl_add_u64 v[10:11], v[6:7], 0, v[8:9]
	v_lshl_add_u64 v[16:17], v[4:5], 0, v[8:9]
	global_load_dwordx4 v[36:39], v[40:41], off offset:32
	global_load_dwordx4 v[32:35], v[40:41], off offset:64
	global_load_dwordx4 v[28:31], v[40:41], off offset:96
	global_load_dwordx4 v[24:27], v[40:41], off offset:128
	global_load_dwordx4 v[20:23], v[40:41], off offset:160
	global_load_dwordx4 v[12:15], v[10:11], off
	global_load_dwordx4 v[4:7], v[16:17], off offset:16
	s_nop 0
	global_load_dwordx4 v[8:11], v[10:11], off offset:16
	s_nop 0
	global_load_dwordx4 v[16:19], v[16:17], off
	s_nop 0
	global_load_dwordx4 v[40:43], v[40:41], off
	s_movk_i32 s0, 0x300
	s_mulk_i32 s18, 0x6000
	v_cmp_gt_i32_e64 s[16:17], s0, v54
	s_mov_b32 s0, 0x2aaaaaab
	s_or_b32 s20, s18, s74
	v_mul_hi_i32 v44, v54, s0
	s_mul_i32 s0, s20, 0xc0
	s_add_u32 s0, s63, s0
	v_lshrrev_b32_e32 v51, 31, v44
	s_addc_u32 s1, s75, 0
	v_ashrrev_i32_e32 v57, 1, v44
	v_lshrrev_b32_e32 v232, 2, v54
	v_and_b32_e32 v233, 3, v54
	v_mul_u32_u24_e32 v232, 0x900, v232
	v_lshl_add_u32 v232, v233, 6, v232
	global_load_dword v239, v232, s[0:1]
	v_lshrrev_b32_e32 v248, 3, v54
	v_and_b32_e32 v249, 7, v54
	v_mul_u32_u24_e32 v248, 0x600, v248
	v_lshl_add_u32 v248, v249, 4, v248
	s_lshl_b32 s100, s20, 7
	s_add_u32 s100, s91, s100
	s_addc_u32 s101, s97, 0
	global_load_dword v250, v248, s[100:101]
	s_barrier
	s_waitcnt vmcnt(10)
	v_fmamk_f32 v3, v1, 0x3c2aaaab, v231
	v_cmp_gt_f32_e64 s[22:23], s11, v3
	s_and_saveexec_b64 s[8:9], s[16:17]
	s_cbranch_execz .LBB0_1157
	v_add_u32_e32 v1, v57, v51
	v_mul_lo_u32 v44, v1, 12
	v_sub_u32_e32 v46, v54, v44
	v_mov_b64_e32 v[44:45], s[0:1]
	v_lshlrev_b32_e32 v46, 3, v46
	v_mad_i64_i32 v[44:45], s[18:19], v1, s70, v[44:45]
	v_ashrrev_i32_e32 v47, 31, v46
	v_lshl_add_u64 v[44:45], v[46:47], 1, v[44:45]
	global_load_dwordx4 v[114:117], v[44:45], off

.LBB0_1607:
	s_cmp_lg_u32 s92, 2
	v_readlane_b32 s14, v253, 12
	s_cselect_b64 s[0:1], -1, 0
	v_readlane_b32 s15, v253, 13
	s_or_b64 s[0:1], s[14:15], s[0:1]
	s_and_b64 s[0:1], s[0:1], exec
	v_readlane_b32 s0, v253, 8
	s_cselect_b32 s0, s9, s0
	s_cmpk_gt_u32 s0, 0x2ff
	s_cbranch_scc1 .LBB0_1602
	s_and_b32 s1, s0, 0xffff
	s_mul_i32 s1, s1, 0xaaab
	s_lshr_b32 s24, s1, 22
	s_mul_i32 s1, s24, 0x60
	s_sub_i32 s0, s0, s1
	s_mul_i32 s1, s0, 0xab
	s_bfe_u32 s18, s1, 0x5000b
	s_mul_i32 s8, s18, 12
	s_sub_i32 s0, s0, s8
	s_and_b32 s93, s0, 0xff
	s_and_b32 s0, s1, 0xf800
	s_lshl_b32 s1, s24, 8
	s_sub_i32 s25, 0x700, s1
	s_or_b32 s64, s0, s25
	s_mul_i32 s0, s64, 12
	s_or_b32 s0, s0, s93
	s_mul_hi_u32 s1, s0, 0xc0
	s_mulk_i32 s0, 0xc0
	s_add_u32 s0, s85, s0
	s_addc_u32 s1, s86, s1
	s_add_i32 s8, s84, s93
	s_mul_i32 s68, s8, 0x4100
	s_lshl_b64 s[8:9], s[68:69], 2
	s_waitcnt vmcnt(0)
	v_mov_b32_e32 v54, v0
	s_add_u32 s8, s87, s8
	s_addc_u32 s9, s88, s9
	v_ashrrev_i32_e32 v52, 6, v54
	s_lshl_b32 s14, s64, 2
	v_and_b32_e32 v55, 31, v54
	v_lshlrev_b32_e32 v53, 5, v52
	s_add_u32 s8, s8, s14
	s_waitcnt lgkmcnt(0)
	v_or_b32_e32 v1, v53, v55
	s_movk_i32 s14, 0x100
	v_cmp_gt_i32_e64 s[14:15], s14, v1
	s_addc_u32 s9, s9, 0
	v_bfe_u32 v56, v54, 5, 1
	v_cndmask_b32_e64 v162, v230, v1, s[14:15]
	v_ashrrev_i32_e32 v163, 31, v162
	v_lshl_add_u64 v[4:5], v[162:163], 2, s[8:9]
	global_load_dword v1, v[4:5], off
	v_mov_b64_e32 v[4:5], s[0:1]
	v_mad_i64_i32 v[4:5], s[0:1], v162, s70, v[4:5]
	v_lshlrev_b32_e32 v50, 4, v56
	v_mov_b32_e32 v51, v2
	v_lshl_add_u64 v[40:41], v[4:5], 0, v[50:51]
	v_add_lshl_u32 v4, v162, s25, 4
	v_ashrrev_i32_e32 v5, 31, v4
	v_lshlrev_b64 v[4:5], 2, v[4:5]
	v_lshl_add_u64 v[6:7], s[6:7], 0, v[4:5]
	v_and_b32_e32 v8, 32, v54
	v_mov_b32_e32 v9, v2
	v_lshl_add_u64 v[4:5], s[62:63], 0, v[4:5]
	v_lshl_add_u64 v[10:11], v[6:7], 0, v[8:9]
	v_lshl_add_u64 v[16:17], v[4:5], 0, v[8:9]
	global_load_dwordx4 v[36:39], v[40:41], off offset:32
	global_load_dwordx4 v[32:35], v[40:41], off offset:64
	global_load_dwordx4 v[28:31], v[40:41], off offset:96
	global_load_dwordx4 v[24:27], v[40:41], off offset:128
	global_load_dwordx4 v[20:23], v[40:41], off offset:160
	global_load_dwordx4 v[12:15], v[10:11], off
	global_load_dwordx4 v[4:7], v[16:17], off offset:16
	s_nop 0
	global_load_dwordx4 v[8:11], v[10:11], off offset:16
	s_nop 0
	global_load_dwordx4 v[16:19], v[16:17], off
	s_nop 0
	global_load_dwordx4 v[40:43], v[40:41], off
	s_movk_i32 s0, 0x300
	s_mulk_i32 s18, 0x6000
	v_cmp_gt_i32_e64 s[16:17], s0, v54
	s_mov_b32 s0, 0x2aaaaaab
	s_or_b32 s20, s18, s93
	v_mul_hi_i32 v44, v54, s0
	s_mul_i32 s0, s20, 0xc0
	s_add_u32 s0, s89, s0
	v_lshrrev_b32_e32 v51, 31, v44
	s_addc_u32 s1, s90, 0
	v_ashrrev_i32_e32 v57, 1, v44
	v_lshrrev_b32_e32 v232, 2, v54
	v_and_b32_e32 v233, 3, v54
	v_mul_u32_u24_e32 v232, 0x900, v232
	v_lshl_add_u32 v232, v233, 6, v232
	global_load_dword v239, v232, s[0:1]
	v_lshrrev_b32_e32 v248, 3, v54
	v_and_b32_e32 v249, 7, v54
	v_mul_u32_u24_e32 v248, 0x600, v248
	v_lshl_add_u32 v248, v249, 4, v248
	s_lshl_b32 s100, s20, 7
	s_add_u32 s100, s91, s100
	s_addc_u32 s101, s94, 0
	global_load_dword v250, v248, s[100:101]
	s_barrier
	s_waitcnt vmcnt(10)
	v_fmamk_f32 v3, v1, 0x3c2aaaab, v231
	v_cmp_gt_f32_e64 s[22:23], s11, v3
	s_and_saveexec_b64 s[8:9], s[16:17]
	s_cbranch_execz .LBB0_1610
	v_add_u32_e32 v1, v57, v51
	v_mul_lo_u32 v44, v1, 12
	v_sub_u32_e32 v46, v54, v44
	v_mov_b64_e32 v[44:45], s[0:1]
	v_lshlrev_b32_e32 v46, 3, v46
	v_mad_i64_i32 v[44:45], s[18:19], v1, s70, v[44:45]
	v_ashrrev_i32_e32 v47, 31, v46
	v_lshl_add_u64 v[44:45], v[46:47], 1, v[44:45]
	global_load_dwordx4 v[114:117], v[44:45], off
